# MLA latent epilogue: Wv^T A-fragment loads: 64 row-per-lane dwordx2 loads -> 32 dwordx4 loads (lane base + hi*8) + v_permlane32_swap pairs that exchange the middle halves
# speedup vs baseline: 1.0237x; 1.0198x over previous
.LBB0_502:
	s_or_b64 exec, exec, s[16:17]
	v_add_f32_e32 v64, v64, v65
	v_fmac_f32_e32 v64, v186, v96
	v_rcp_f32_e32 v67, v64
	s_lshl_b64 s[14:15], s[14:15], 12
	s_add_u32 s14, s23, s14
	s_addc_u32 s15, s24, s15
	v_mul_f32_e32 v16, v67, v16
	v_mul_f32_e32 v17, v67, v17
	v_cvt_pk_bf16_f32 v80, v16, v17
	v_mul_f32_e32 v16, v67, v18
	v_mul_f32_e32 v17, v67, v19
	v_cvt_pk_bf16_f32 v81, v16, v17
	v_mul_f32_e32 v16, v67, v20
	v_mul_f32_e32 v17, v67, v21
	v_cvt_pk_bf16_f32 v82, v16, v17
	v_mul_f32_e32 v16, v67, v22
	v_mul_f32_e32 v17, v67, v23
	v_cvt_pk_bf16_f32 v83, v16, v17
	v_mul_f32_e32 v16, v67, v24
	v_mul_f32_e32 v17, v67, v25
	v_cvt_pk_bf16_f32 v84, v16, v17
	v_mul_f32_e32 v16, v67, v26
	v_mul_f32_e32 v17, v67, v27
	v_cvt_pk_bf16_f32 v85, v16, v17
	v_mul_f32_e32 v16, v67, v28
	v_mul_f32_e32 v17, v67, v29
	v_cvt_pk_bf16_f32 v86, v16, v17
	v_mul_f32_e32 v16, v67, v30
	v_mul_f32_e32 v17, v67, v31
	v_cvt_pk_bf16_f32 v87, v16, v17
	v_mul_f32_e32 v16, v67, v32
	v_mul_f32_e32 v17, v67, v33
	v_cvt_pk_bf16_f32 v88, v16, v17
	v_mul_f32_e32 v16, v67, v34
	v_mul_f32_e32 v17, v67, v35
	v_cvt_pk_bf16_f32 v89, v16, v17
	v_mul_f32_e32 v16, v67, v36
	v_mul_f32_e32 v17, v67, v37
	v_cvt_pk_bf16_f32 v90, v16, v17
	v_mul_f32_e32 v16, v67, v38
	v_mul_f32_e32 v17, v67, v39
	v_cvt_pk_bf16_f32 v91, v16, v17
	v_mul_f32_e32 v16, v67, v40
	v_mul_f32_e32 v17, v67, v41
	v_cvt_pk_bf16_f32 v92, v16, v17
	v_mul_f32_e32 v16, v67, v42
	v_mul_f32_e32 v17, v67, v43
	v_cvt_pk_bf16_f32 v93, v16, v17
	v_mul_f32_e32 v16, v67, v44
	v_mul_f32_e32 v17, v67, v45
	v_cvt_pk_bf16_f32 v94, v16, v17
	v_mul_f32_e32 v16, v67, v46
	v_mul_f32_e32 v17, v67, v47
	v_cvt_pk_bf16_f32 v95, v16, v17
	v_mul_f32_e32 v16, v67, v48
	v_mul_f32_e32 v17, v67, v49
	v_cvt_pk_bf16_f32 v76, v16, v17
	v_mul_f32_e32 v16, v67, v50
	v_mul_f32_e32 v17, v67, v51
	v_cvt_pk_bf16_f32 v77, v16, v17
	v_mul_f32_e32 v16, v67, v52
	v_mul_f32_e32 v17, v67, v53
	v_cvt_pk_bf16_f32 v78, v16, v17
	v_mul_f32_e32 v16, v67, v54
	v_mul_f32_e32 v17, v67, v55
	v_cvt_pk_bf16_f32 v79, v16, v17
	v_mul_f32_e32 v16, v67, v56
	v_mul_f32_e32 v17, v67, v57
	v_cvt_pk_bf16_f32 v72, v16, v17
	v_mul_f32_e32 v16, v67, v58
	v_mul_f32_e32 v17, v67, v59
	v_cvt_pk_bf16_f32 v73, v16, v17
	v_mul_f32_e32 v16, v67, v60
	v_mul_f32_e32 v17, v67, v61
	v_mul_f32_e32 v0, v67, v0
	v_mul_f32_e32 v1, v67, v1
	v_cvt_pk_bf16_f32 v74, v16, v17
	v_mul_f32_e32 v16, v67, v62
	v_mul_f32_e32 v17, v67, v63
	v_cvt_pk_bf16_f32 v75, v16, v17
	v_cvt_pk_bf16_f32 v68, v0, v1
	v_mul_f32_e32 v0, v67, v2
	v_mul_f32_e32 v1, v67, v3
	v_cvt_pk_bf16_f32 v69, v0, v1
	v_mul_f32_e32 v0, v67, v4
	v_mul_f32_e32 v1, v67, v5
	v_cvt_pk_bf16_f32 v70, v0, v1
	v_mul_f32_e32 v0, v67, v6
	v_mul_f32_e32 v1, v67, v7
	s_lshl_b32 s16, s0, 8
	v_cvt_pk_bf16_f32 v71, v0, v1
	v_mul_f32_e32 v0, v67, v8
	v_mul_f32_e32 v1, v67, v9
	s_add_u32 s14, s14, s16
	v_cvt_pk_bf16_f32 v64, v0, v1
	v_mul_f32_e32 v0, v67, v10
	v_mul_f32_e32 v1, v67, v11
	s_addc_u32 s15, s15, 0
	v_cvt_pk_bf16_f32 v65, v0, v1
	v_mul_f32_e32 v0, v67, v12
	v_mul_f32_e32 v1, v67, v13
	s_lshl_b32 s0, s0, 15
	v_cvt_pk_bf16_f32 v66, v0, v1
	v_mul_f32_e32 v0, v67, v14
	v_mul_f32_e32 v1, v67, v15
	v_lshl_add_u64 v[62:63], v[152:153], 0, s[0:1]
	v_lshlrev_b32_e32 v194, 3, v172
	v_mov_b32_e32 v195, 0
	v_lshl_add_u64 v[62:63], v[62:63], 0, v[194:195]
	v_cvt_pk_bf16_f32 v67, v0, v1
	global_load_dwordx4 v[0:3], v[62:63], off
	global_load_dwordx4 v[16:19], v[62:63], off offset:32
	global_load_dwordx4 v[20:23], v[62:63], off offset:64
	global_load_dwordx4 v[24:27], v[62:63], off offset:96
	global_load_dwordx4 v[28:31], v[62:63], off offset:128
	v_add_co_u32_e32 v48, vcc, s36, v62
	s_waitcnt vmcnt(0)
	v_permlane32_swap_b32_e32 v0, v2
	v_permlane32_swap_b32_e32 v1, v3
	v_permlane32_swap_b32_e32 v16, v18
	v_permlane32_swap_b32_e32 v17, v19
	v_permlane32_swap_b32_e32 v20, v22
	v_permlane32_swap_b32_e32 v21, v23
	v_permlane32_swap_b32_e32 v24, v26
	v_permlane32_swap_b32_e32 v25, v27
	v_permlane32_swap_b32_e32 v28, v30
	v_permlane32_swap_b32_e32 v29, v31
	s_nop 1
	v_mfma_f32_32x32x16_bf16 v[0:15], v[0:3], v[80:83], 0
	v_addc_co_u32_e32 v49, vcc, 0, v63, vcc
	v_add_co_u32_e32 v138, vcc, s37, v62
	s_add_i32 s41, s41, s60
	s_nop 0
	v_addc_co_u32_e32 v139, vcc, 0, v63, vcc
	v_mfma_f32_32x32x16_bf16 v[0:15], v[16:19], v[84:87], v[0:15]
	global_load_dwordx4 v[16:19], v[62:63], off offset:160
	v_add_co_u32_e32 v146, vcc, s40, v62
	s_cmpk_gt_i32 s41, 0x7ff
	s_nop 0
	v_addc_co_u32_e32 v147, vcc, 0, v63, vcc
	v_mfma_f32_32x32x16_bf16 v[0:15], v[20:23], v[88:91], v[0:15]
	global_load_dwordx4 v[20:23], v[62:63], off offset:192
	v_mfma_f32_32x32x16_bf16 v[0:15], v[24:27], v[92:95], v[0:15]
	global_load_dwordx4 v[24:27], v[48:49], off
	global_load_dwordx4 v[32:35], v[62:63], off offset:224
	global_load_dwordx4 v[36:39], v[48:49], off offset:32
	global_load_dwordx4 v[40:43], v[48:49], off offset:64
	global_load_dwordx4 v[44:47], v[48:49], off offset:96
	v_lshl_add_u64 v[62:63], s[14:15], 0, v[154:155]
	v_lshl_add_u64 v[96:97], v[62:63], 0, v[150:151]
	v_lshlrev_b32_e32 v198, 3, v172
	v_mov_b32_e32 v199, 0
	v_lshl_add_u64 v[198:199], v[96:97], 0, v[198:199]
	v_mfma_f32_32x32x16_bf16 v[0:15], v[28:31], v[76:79], v[0:15]
	s_waitcnt vmcnt(0)
	v_permlane32_swap_b32_e32 v16, v18
	v_permlane32_swap_b32_e32 v17, v19
	v_permlane32_swap_b32_e32 v20, v22
	v_permlane32_swap_b32_e32 v21, v23
	v_permlane32_swap_b32_e32 v24, v26
	v_permlane32_swap_b32_e32 v25, v27
	v_permlane32_swap_b32_e32 v32, v34
	v_permlane32_swap_b32_e32 v33, v35
	v_permlane32_swap_b32_e32 v36, v38
	v_permlane32_swap_b32_e32 v37, v39
	v_permlane32_swap_b32_e32 v40, v42
	v_permlane32_swap_b32_e32 v41, v43
	v_permlane32_swap_b32_e32 v44, v46
	v_permlane32_swap_b32_e32 v45, v47
	s_nop 1
	v_mfma_f32_32x32x16_bf16 v[0:15], v[16:19], v[72:75], v[0:15]
	v_mfma_f32_32x32x16_bf16 v[0:15], v[20:23], v[68:71], v[0:15]
	v_mfma_f32_32x32x16_bf16 v[0:15], v[32:35], v[64:67], v[0:15]
	global_load_dwordx4 v[32:35], v[138:139], off
	global_load_dwordx4 v[50:53], v[138:139], off offset:32
	global_load_dwordx4 v[54:57], v[138:139], off offset:64
	global_load_dwordx4 v[58:61], v[138:139], off offset:96
	global_load_dwordx4 v[98:101], v[146:147], off
	global_load_dwordx4 v[102:105], v[146:147], off offset:32
	global_load_dwordx4 v[106:109], v[146:147], off offset:64
	global_load_dwordx2 v[158:159], v[96:97], off
	v_mfma_f32_32x32x16_bf16 v[16:31], v[24:27], v[80:83], 0
	global_load_dwordx4 v[110:113], v[146:147], off offset:96
	global_load_dwordx4 v[114:117], v[48:49], off offset:128
	global_load_dwordx4 v[118:121], v[48:49], off offset:160
	global_load_dwordx4 v[122:125], v[48:49], off offset:192
	global_load_dwordx4 v[126:129], v[48:49], off offset:224
	global_load_dwordx4 v[130:133], v[138:139], off offset:128
	global_load_dwordx4 v[134:137], v[138:139], off offset:160
	v_mfma_f32_32x32x16_bf16 v[16:31], v[36:39], v[84:87], v[16:31]
	v_mfma_f32_32x32x16_bf16 v[16:31], v[40:43], v[88:91], v[16:31]
	v_mfma_f32_32x32x16_bf16 v[16:31], v[44:47], v[92:95], v[16:31]
	s_waitcnt vmcnt(0)
	v_permlane32_swap_b32_e32 v32, v34
	v_permlane32_swap_b32_e32 v33, v35
	v_permlane32_swap_b32_e32 v50, v52
	v_permlane32_swap_b32_e32 v51, v53
	v_permlane32_swap_b32_e32 v54, v56
	v_permlane32_swap_b32_e32 v55, v57
	v_permlane32_swap_b32_e32 v58, v60
	v_permlane32_swap_b32_e32 v59, v61
	v_permlane32_swap_b32_e32 v98, v100
	v_permlane32_swap_b32_e32 v99, v101
	v_permlane32_swap_b32_e32 v102, v104
	v_permlane32_swap_b32_e32 v103, v105
	v_permlane32_swap_b32_e32 v106, v108
	v_permlane32_swap_b32_e32 v107, v109
	v_permlane32_swap_b32_e32 v110, v112
	v_permlane32_swap_b32_e32 v111, v113
	v_permlane32_swap_b32_e32 v114, v116
	v_permlane32_swap_b32_e32 v115, v117
	v_permlane32_swap_b32_e32 v118, v120
	v_permlane32_swap_b32_e32 v119, v121
	v_permlane32_swap_b32_e32 v122, v124
	v_permlane32_swap_b32_e32 v123, v125
	v_permlane32_swap_b32_e32 v126, v128
	v_permlane32_swap_b32_e32 v127, v129
	v_permlane32_swap_b32_e32 v130, v132
	v_permlane32_swap_b32_e32 v131, v133
	v_permlane32_swap_b32_e32 v134, v136
	v_permlane32_swap_b32_e32 v135, v137
	s_nop 1
	v_mfma_f32_32x32x16_bf16 v[32:47], v[32:35], v[80:83], 0
	v_mfma_f32_32x32x16_bf16 v[32:47], v[50:53], v[84:87], v[32:47]
	v_mfma_f32_32x32x16_bf16 v[32:47], v[54:57], v[88:91], v[32:47]
	v_mfma_f32_32x32x16_bf16 v[32:47], v[58:61], v[92:95], v[32:47]
	v_mfma_f32_32x32x16_bf16 v[48:63], v[98:101], v[80:83], 0
	global_load_dwordx4 v[80:83], v[138:139], off offset:192
	global_load_dwordx4 v[98:101], v[138:139], off offset:224
	s_nop 0
	global_load_dwordx4 v[138:141], v[146:147], off offset:128
	global_load_dwordx4 v[142:145], v[146:147], off offset:160
	v_mfma_f32_32x32x16_bf16 v[48:63], v[102:105], v[84:87], v[48:63]
	global_load_dwordx4 v[84:87], v[146:147], off offset:192
	global_load_dwordx4 v[102:105], v[146:147], off offset:224
	v_lshlrev_b32_e32 v146, 16, v158
	v_and_b32_e32 v147, 0xffff0000, v158
	v_lshlrev_b32_e32 v158, 16, v159
	v_mul_f32_e32 v0, v0, v146
	v_mul_f32_e32 v1, v1, v147
	v_cvt_pk_bf16_f32 v0, v0, v1
	v_mfma_f32_32x32x16_bf16 v[48:63], v[106:109], v[88:91], v[48:63]
	v_and_b32_e32 v88, 0xffff0000, v159
	v_mul_f32_e32 v1, v2, v158
	v_mul_f32_e32 v2, v3, v88
	v_cvt_pk_bf16_f32 v1, v1, v2
	s_nop 0
	v_mov_b32_e32 v200, v0
	v_mov_b32_e32 v201, v1
	v_mfma_f32_32x32x16_bf16 v[16:31], v[114:117], v[76:79], v[16:31]
	s_waitcnt vmcnt(0)
	v_permlane32_swap_b32_e32 v80, v82
	v_permlane32_swap_b32_e32 v81, v83
	v_permlane32_swap_b32_e32 v98, v100
	v_permlane32_swap_b32_e32 v99, v101
	v_permlane32_swap_b32_e32 v138, v140
	v_permlane32_swap_b32_e32 v139, v141
	v_permlane32_swap_b32_e32 v142, v144
	v_permlane32_swap_b32_e32 v143, v145
	v_permlane32_swap_b32_e32 v84, v86
	v_permlane32_swap_b32_e32 v85, v87
	v_permlane32_swap_b32_e32 v102, v104
	v_permlane32_swap_b32_e32 v103, v105
	s_nop 1
	v_lshlrev_b32_e32 v0, 16, v208
	v_and_b32_e32 v1, 0xffff0000, v208
	v_lshlrev_b32_e32 v2, 16, v209
	v_and_b32_e32 v3, 0xffff0000, v209
	v_mul_f32_e32 v0, v4, v0
	v_mul_f32_e32 v1, v5, v1
	v_mul_f32_e32 v2, v6, v2
	v_mul_f32_e32 v3, v7, v3
	v_cvt_pk_bf16_f32 v0, v0, v1
	v_cvt_pk_bf16_f32 v1, v2, v3
	v_mfma_f32_32x32x16_bf16 v[16:31], v[118:121], v[72:75], v[16:31]
	v_mov_b32_e32 v202, v0
	v_mov_b32_e32 v203, v1
	s_nop 1
	v_permlane32_swap_b32_e32 v200, v202
	v_permlane32_swap_b32_e32 v201, v203
	global_store_dwordx4 v[198:199], v[200:203], off
	v_lshlrev_b32_e32 v0, 16, v210
	v_and_b32_e32 v1, 0xffff0000, v210
	v_lshlrev_b32_e32 v2, 16, v211
	v_and_b32_e32 v3, 0xffff0000, v211
	v_mul_f32_e32 v0, v8, v0
	v_mul_f32_e32 v1, v9, v1
	v_mul_f32_e32 v2, v10, v2
	v_mul_f32_e32 v3, v11, v3
	v_cvt_pk_bf16_f32 v0, v0, v1
	v_cvt_pk_bf16_f32 v1, v2, v3
	v_mfma_f32_32x32x16_bf16 v[16:31], v[122:125], v[68:71], v[16:31]
	v_mov_b32_e32 v200, v0
	v_mov_b32_e32 v201, v1
	v_lshlrev_b32_e32 v0, 16, v212
	v_and_b32_e32 v1, 0xffff0000, v212
	v_lshlrev_b32_e32 v2, 16, v213
	v_and_b32_e32 v3, 0xffff0000, v213
	v_mul_f32_e32 v0, v12, v0
	v_mul_f32_e32 v1, v13, v1
	v_mul_f32_e32 v2, v14, v2
	v_mul_f32_e32 v3, v15, v3
	v_cvt_pk_bf16_f32 v0, v0, v1
	v_cvt_pk_bf16_f32 v1, v2, v3
	v_mfma_f32_32x32x16_bf16 v[16:31], v[126:129], v[64:67], v[16:31]
	v_mov_b32_e32 v202, v0
	v_mov_b32_e32 v203, v1
	s_nop 1
	v_permlane32_swap_b32_e32 v200, v202
	v_permlane32_swap_b32_e32 v201, v203
	global_store_dwordx4 v[198:199], v[200:203], off offset:32
	v_lshlrev_b32_e32 v0, 16, v214
	v_and_b32_e32 v1, 0xffff0000, v214
	v_lshlrev_b32_e32 v2, 16, v215
	v_and_b32_e32 v3, 0xffff0000, v215
	s_nop 5
	v_mul_f32_e32 v0, v16, v0
	v_mul_f32_e32 v1, v17, v1
	v_mul_f32_e32 v2, v18, v2
	v_mul_f32_e32 v3, v19, v3
	v_cvt_pk_bf16_f32 v0, v0, v1
	v_cvt_pk_bf16_f32 v1, v2, v3
	v_mfma_f32_32x32x16_bf16 v[32:47], v[130:133], v[76:79], v[32:47]
	v_mov_b32_e32 v200, v0
	v_mov_b32_e32 v201, v1
	v_lshlrev_b32_e32 v0, 16, v216
	v_and_b32_e32 v1, 0xffff0000, v216
	v_lshlrev_b32_e32 v2, 16, v217
	v_and_b32_e32 v3, 0xffff0000, v217
	v_mul_f32_e32 v0, v20, v0
	v_mul_f32_e32 v1, v21, v1
	v_mul_f32_e32 v2, v22, v2
	v_mul_f32_e32 v3, v23, v3
	v_cvt_pk_bf16_f32 v0, v0, v1
	v_cvt_pk_bf16_f32 v1, v2, v3
	v_mfma_f32_32x32x16_bf16 v[32:47], v[134:137], v[72:75], v[32:47]
	v_mov_b32_e32 v202, v0
	v_mov_b32_e32 v203, v1
	s_nop 1
	v_permlane32_swap_b32_e32 v200, v202
	v_permlane32_swap_b32_e32 v201, v203
	global_store_dwordx4 v[198:199], v[200:203], off offset:64
	v_lshlrev_b32_e32 v0, 16, v218
	v_and_b32_e32 v1, 0xffff0000, v218
	v_lshlrev_b32_e32 v2, 16, v219
	v_and_b32_e32 v3, 0xffff0000, v219
	v_mul_f32_e32 v0, v24, v0
	v_mul_f32_e32 v1, v25, v1
	v_mul_f32_e32 v2, v26, v2
	v_mul_f32_e32 v3, v27, v3
	v_cvt_pk_bf16_f32 v0, v0, v1
	v_cvt_pk_bf16_f32 v1, v2, v3
	v_mfma_f32_32x32x16_bf16 v[32:47], v[80:83], v[68:71], v[32:47]
	v_mov_b32_e32 v200, v0
	v_mov_b32_e32 v201, v1
	v_lshlrev_b32_e32 v0, 16, v220
	v_and_b32_e32 v1, 0xffff0000, v220
	v_lshlrev_b32_e32 v2, 16, v221
	v_and_b32_e32 v3, 0xffff0000, v221
	v_mul_f32_e32 v0, v28, v0
	v_mul_f32_e32 v1, v29, v1
	v_mul_f32_e32 v2, v30, v2
	v_mul_f32_e32 v3, v31, v3
	v_cvt_pk_bf16_f32 v0, v0, v1
	v_cvt_pk_bf16_f32 v1, v2, v3
	v_mfma_f32_32x32x16_bf16 v[32:47], v[98:101], v[64:67], v[32:47]
	v_mov_b32_e32 v202, v0
	v_mov_b32_e32 v203, v1
	s_nop 1
	v_permlane32_swap_b32_e32 v200, v202
	v_permlane32_swap_b32_e32 v201, v203
	global_store_dwordx4 v[198:199], v[200:203], off offset:96
	v_lshlrev_b32_e32 v0, 16, v222
	v_and_b32_e32 v1, 0xffff0000, v222
	v_lshlrev_b32_e32 v2, 16, v223
	v_and_b32_e32 v3, 0xffff0000, v223
	s_nop 5
	v_mul_f32_e32 v0, v32, v0
	v_mul_f32_e32 v1, v33, v1
	v_mul_f32_e32 v2, v34, v2
	v_mul_f32_e32 v3, v35, v3
	v_cvt_pk_bf16_f32 v0, v0, v1
	v_cvt_pk_bf16_f32 v1, v2, v3
	v_mfma_f32_32x32x16_bf16 v[48:63], v[110:113], v[92:95], v[48:63]
	v_mov_b32_e32 v200, v0
	v_mov_b32_e32 v201, v1
	v_lshlrev_b32_e32 v0, 16, v224
	v_and_b32_e32 v1, 0xffff0000, v224
	v_lshlrev_b32_e32 v2, 16, v225
	v_and_b32_e32 v3, 0xffff0000, v225
	v_mul_f32_e32 v0, v36, v0
	v_mul_f32_e32 v1, v37, v1
	v_mul_f32_e32 v2, v38, v2
	v_mul_f32_e32 v3, v39, v3
	v_cvt_pk_bf16_f32 v0, v0, v1
	v_cvt_pk_bf16_f32 v1, v2, v3
	v_mfma_f32_32x32x16_bf16 v[48:63], v[138:141], v[76:79], v[48:63]
	v_mov_b32_e32 v202, v0
	v_mov_b32_e32 v203, v1
	s_nop 1
	v_permlane32_swap_b32_e32 v200, v202
	v_permlane32_swap_b32_e32 v201, v203
	global_store_dwordx4 v[198:199], v[200:203], off offset:128
	v_lshlrev_b32_e32 v0, 16, v226
	v_and_b32_e32 v1, 0xffff0000, v226
	v_lshlrev_b32_e32 v2, 16, v227
	v_and_b32_e32 v3, 0xffff0000, v227
	v_mul_f32_e32 v0, v40, v0
	v_mul_f32_e32 v1, v41, v1
	v_mul_f32_e32 v2, v42, v2
	v_mul_f32_e32 v3, v43, v3
	v_cvt_pk_bf16_f32 v0, v0, v1
	v_cvt_pk_bf16_f32 v1, v2, v3
	v_mfma_f32_32x32x16_bf16 v[48:63], v[142:145], v[72:75], v[48:63]
	v_mov_b32_e32 v200, v0
	v_mov_b32_e32 v201, v1
	v_lshlrev_b32_e32 v0, 16, v228
	v_and_b32_e32 v1, 0xffff0000, v228
	v_lshlrev_b32_e32 v2, 16, v229
	v_and_b32_e32 v3, 0xffff0000, v229
	v_mul_f32_e32 v0, v44, v0
	v_mul_f32_e32 v1, v45, v1
	v_mul_f32_e32 v2, v46, v2
	v_mul_f32_e32 v3, v47, v3
	v_cvt_pk_bf16_f32 v0, v0, v1
	v_cvt_pk_bf16_f32 v1, v2, v3
	v_mfma_f32_32x32x16_bf16 v[48:63], v[84:87], v[68:71], v[48:63]
	v_mov_b32_e32 v202, v0
	v_mov_b32_e32 v203, v1
	s_nop 1
	v_permlane32_swap_b32_e32 v200, v202
	v_permlane32_swap_b32_e32 v201, v203
	global_store_dwordx4 v[198:199], v[200:203], off offset:160
	v_lshlrev_b32_e32 v0, 16, v230
	v_mfma_f32_32x32x16_bf16 v[48:63], v[102:105], v[64:67], v[48:63]
	v_and_b32_e32 v1, 0xffff0000, v230
	v_lshlrev_b32_e32 v2, 16, v231
	v_and_b32_e32 v3, 0xffff0000, v231
	s_nop 8
	v_mul_f32_e32 v0, v48, v0
	v_mul_f32_e32 v1, v49, v1
	v_mul_f32_e32 v2, v50, v2
	v_mul_f32_e32 v3, v51, v3
	v_cvt_pk_bf16_f32 v0, v0, v1
	v_cvt_pk_bf16_f32 v1, v2, v3
	s_nop 0
	v_mov_b32_e32 v200, v0
	v_mov_b32_e32 v201, v1
	v_lshlrev_b32_e32 v0, 16, v232
	v_and_b32_e32 v1, 0xffff0000, v232
	v_lshlrev_b32_e32 v2, 16, v233
	v_and_b32_e32 v3, 0xffff0000, v233
	v_mul_f32_e32 v0, v52, v0
	v_mul_f32_e32 v1, v53, v1
	v_mul_f32_e32 v2, v54, v2
	v_mul_f32_e32 v3, v55, v3
	v_cvt_pk_bf16_f32 v0, v0, v1
	v_cvt_pk_bf16_f32 v1, v2, v3
	s_nop 0
	v_mov_b32_e32 v202, v0
	v_mov_b32_e32 v203, v1
	s_nop 1
	v_permlane32_swap_b32_e32 v200, v202
	v_permlane32_swap_b32_e32 v201, v203
	global_store_dwordx4 v[198:199], v[200:203], off offset:192
	v_lshlrev_b32_e32 v0, 16, v234
	v_and_b32_e32 v1, 0xffff0000, v234
	v_lshlrev_b32_e32 v2, 16, v235
	v_and_b32_e32 v3, 0xffff0000, v235
	v_mul_f32_e32 v0, v56, v0
	v_mul_f32_e32 v1, v57, v1
	v_mul_f32_e32 v2, v58, v2
	v_mul_f32_e32 v3, v59, v3
	v_cvt_pk_bf16_f32 v0, v0, v1
	v_cvt_pk_bf16_f32 v1, v2, v3
	s_nop 0
	v_mov_b32_e32 v200, v0
	v_mov_b32_e32 v201, v1
	v_lshlrev_b32_e32 v0, 16, v236
	v_and_b32_e32 v1, 0xffff0000, v236
	v_lshlrev_b32_e32 v2, 16, v237
	v_and_b32_e32 v3, 0xffff0000, v237
	v_mul_f32_e32 v0, v60, v0
	v_mul_f32_e32 v1, v61, v1
	v_mul_f32_e32 v2, v62, v2
	v_mul_f32_e32 v3, v63, v3
	v_cvt_pk_bf16_f32 v0, v0, v1
	v_cvt_pk_bf16_f32 v1, v2, v3
	v_mov_b32_e32 v202, v0
	v_mov_b32_e32 v203, v1
	s_nop 1
	v_permlane32_swap_b32_e32 v200, v202
	v_permlane32_swap_b32_e32 v201, v203
	global_store_dwordx4 v[198:199], v[200:203], off offset:224
	s_waitcnt lgkmcnt(0)
	s_barrier
	s_cbranch_scc1 .LBB0_525
